# mix_b compaction loop: software-prefetch next 64 keys from LDS
# speedup vs baseline: 1.3402x; 1.0051x over previous
; DI void phase_mix_b(int wv_, int vb_, int nvb_, char* ws_, const Ctx& p, char* smem) {
;     ...
;       } else {
;         int eqseen = 0;
;         const unsigned long long lt = (1ull << lane) - 1ull;
;         for (int j0 = 0; j0 < n; j0 += 64) {
;           const int j = j0 + lane; const bool v = j < n;
;           unsigned u = v ? (unsigned)myS[j] : 0u;
;           const bool gt = v && (u > prefix), eq = v && (u == prefix);
;           unsigned long long be = __ballot(eq);
;           const bool take = gt || (eq && (eqseen + __popcll(be & lt) < need));
;           unsigned long long bt = __ballot(take);
;           int pos = cnt + __popcll(bt & lt);
;           if (take && pos < 256) mySel[pos] = (u16)j;
;           cnt += __popcll(bt); eqseen += __popcll(be);
;         }
.LBB0_429:
	v_lshl_add_u32 v4, v0, 1, v130
	v_cmp_lt_i32_e32 vcc, s22, v6
	v_lshlrev_b32_e32 v2, 1, v7
	s_and_saveexec_b64 s[2:3], vcc
	s_xor_b64 s[10:11], exec, s[2:3]
	s_cbranch_execz .LBB0_437
	v_lshlrev_b64 v[2:3], v7, -1
	v_not_b32_e32 v0, v2
	v_lshlrev_b32_e32 v2, 1, v7
	v_not_b32_e32 v3, v3
	v_add3_u32 v5, v12, v2, v214
	s_mov_b32 s14, 0
	s_mov_b64 s[12:13], 0
	s_mov_b32 s15, 0
	s_mov_b32 s18, 0
	ds_read_u16 v160, v5
	s_branch .LBB0_432

; DI void phase_mix_b(int wv_, int vb_, int nvb_, char* ws_, const Ctx& p, char* smem) {
;     ...
;         for (int j0 = 0; j0 < n; j0 += 64) {
;           const int j = j0 + lane; const bool v = j < n;
;           unsigned u = v ? (unsigned)myS[j] : 0u;
;           const bool gt = v && (u > prefix), eq = v && (u == prefix);
;           unsigned long long be = __ballot(eq);
;           const bool take = gt || (eq && (eqseen + __popcll(be & lt) < need));
;           unsigned long long bt = __ballot(take);
;           int pos = cnt + __popcll(bt & lt);
;           if (take && pos < 256) mySel[pos] = (u16)j;
;           cnt += __popcll(bt); eqseen += __popcll(be);
;         }
.LBB0_432:
	v_add_u32_e32 v12, s14, v7
	v_cmp_le_i32_e64 s[2:3], v12, v6
	s_waitcnt lgkmcnt(0)
	s_nop 0
	v_cndmask_b32_e64 v13, 0, v160, s[2:3]
	ds_read_u16 v160, v5 offset:128
	v_cmp_eq_u32_e64 s[6:7], v13, v11
	s_and_b64 s[8:9], s[2:3], s[6:7]
	v_cmp_gt_u32_e64 s[4:5], v13, v11
	v_cndmask_b32_e64 v13, 0, 1, s[8:9]
	v_cmp_ne_u32_e32 vcc, 0, v13
	s_nop 1
	v_and_b32_e32 v14, vcc_lo, v0
	v_and_b32_e32 v13, vcc_hi, v3
	v_bcnt_u32_b32 v14, v14, 0
	v_bcnt_u32_b32 v13, v13, v14
	v_add_u32_e32 v13, s15, v13
	v_cmp_lt_u32_e64 s[8:9], v13, v10
	v_cndmask_b32_e64 v14, 0, 1, s[4:5]
	s_nop 0
	v_cndmask_b32_e64 v13, 0, 1, s[8:9]
	v_cndmask_b32_e64 v13, v14, v13, s[6:7]
	v_and_b32_e32 v13, 1, v13
	v_cmp_eq_u32_e64 s[4:5], 1, v13
	s_and_b64 s[6:7], s[2:3], s[4:5]
	v_cndmask_b32_e64 v13, 0, 1, s[6:7]
	v_cmp_ne_u32_e64 s[2:3], 0, v13
	s_movk_i32 s4, 0x100
	s_nop 0
	v_and_b32_e32 v14, s2, v0
	v_and_b32_e32 v13, s3, v3
	v_bcnt_u32_b32 v14, v14, 0
	v_bcnt_u32_b32 v13, v13, v14
	v_add_u32_e32 v13, s18, v13
	v_cmp_gt_i32_e64 s[4:5], s4, v13
	s_and_b64 s[6:7], s[6:7], s[4:5]
	s_and_saveexec_b64 s[4:5], s[6:7]
	s_cbranch_execz .LBB0_431
	v_lshl_add_u32 v13, v13, 1, v4
	ds_write_b16 v13, v12
	s_branch .LBB0_431
